# code after prep moved +32 bytes (s_nop padding): placement of the hot loops
# speedup vs baseline: 1.0052x; 1.0052x over previous
.LBB0_30:
	global_load_dword v75, v[66:67], off
	global_load_dword v76, v[68:69], off
	global_load_dword v77, v[70:71], off
	global_load_dword v78, v[72:73], off
	v_and_b32_e32 v79, 0x7e, v0
	s_add_i32 s14, 0, 0x10200
	v_lshl_or_b32 v80, v0, 2, 4
	v_lshl_add_u32 v79, v79, 2, s14
	v_add_u32_e32 v80, s14, v80
	ds_read_b32 v79, v79
	ds_read_b32 v80, v80
	v_add_co_u32_e32 v64, vcc, 0x200, v64
	s_xor_b64 s[14:15], vcc, -1
	s_and_b64 s[14:15], exec, s[14:15]
	v_add_u32_e32 v0, 64, v0
	v_lshl_add_u64 v[66:67], v[66:67], 0, s[44:45]
	v_lshl_add_u64 v[68:69], v[68:69], 0, s[44:45]
	v_lshl_add_u64 v[70:71], v[70:71], 0, s[44:45]
	v_lshl_add_u64 v[72:73], v[72:73], 0, s[44:45]
	s_or_b64 s[0:1], s[14:15], s[0:1]
	s_waitcnt vmcnt(2) lgkmcnt(0)
	v_mul_f32_e32 v81, v76, v80
	v_mul_f32_e32 v80, v75, v80
	v_fma_f32 v75, v75, v79, -v81
	v_fmac_f32_e32 v80, v76, v79
	s_waitcnt vmcnt(0)
	ds_write2st64_b32 v74, v77, v78 offset0:32 offset1:48
	ds_write2st64_b32 v74, v75, v80 offset1:16
	v_add_u32_e32 v74, 0x800, v74
	s_andn2_b64 exec, exec, s[0:1]
	s_cbranch_execnz .LBB0_30
	s_or_b64 exec, exec, s[0:1]
	s_ashr_i32 s64, s62, 5
	s_and_b32 s43, s62, 31
	s_lshl_b32 s0, s64, 9
	s_lshl_b32 s1, s43, 4
	s_or_b32 s46, s1, s0
	s_mov_b64 s[0:1], 0
	v_mov_b32_e32 v0, v88
	v_mov_b32_e32 v64, v173
	s_waitcnt lgkmcnt(0)
	s_barrier
	ds_read_b128 v[100:103], v90 offset:0
	ds_read_b128 v[104:107], v90 offset:16
	ds_read_b128 v[108:111], v90 offset:4096
	ds_read_b128 v[112:115], v90 offset:4112
	v_add_u32_e32 v78, 0, v89
	v_add_u32_e32 v79, 0x1000, v78
	ds_read2_b32 v[116:117], v78 offset0:0 offset1:16
	ds_read2_b32 v[118:119], v78 offset0:32 offset1:48
	ds_read2_b32 v[120:121], v78 offset0:64 offset1:80
	ds_read2_b32 v[122:123], v78 offset0:96 offset1:112
	ds_read2_b32 v[70:71], v79 offset0:0 offset1:16
	ds_read2_b32 v[72:73], v79 offset0:32 offset1:48
	ds_read2_b32 v[74:75], v79 offset0:64 offset1:80
	ds_read2_b32 v[76:77], v79 offset0:96 offset1:112
	s_waitcnt lgkmcnt(0)
	v_mul_f32_e32 v66, v108, v70
	v_mul_f32_e32 v68, v100, v70
	v_fma_f32 v124, v100, v116, -v66
	v_fma_f32 v125, v108, v116, v68
	v_mul_f32_e32 v66, v109, v71
	v_mul_f32_e32 v68, v101, v71
	v_fma_f32 v126, v101, v117, -v66
	v_fma_f32 v127, v109, v117, v68
	v_mul_f32_e32 v66, v110, v72
	v_mul_f32_e32 v68, v102, v72
	v_fma_f32 v128, v102, v118, -v66
	v_fma_f32 v129, v110, v118, v68
	v_mul_f32_e32 v66, v111, v73
	v_mul_f32_e32 v68, v103, v73
	v_fma_f32 v130, v103, v119, -v66
	v_fma_f32 v131, v111, v119, v68
	v_mul_f32_e32 v66, v112, v74
	v_mul_f32_e32 v68, v104, v74
	v_fma_f32 v132, v104, v120, -v66
	v_fma_f32 v133, v112, v120, v68
	v_mul_f32_e32 v66, v113, v75
	v_mul_f32_e32 v68, v105, v75
	v_fma_f32 v134, v105, v121, -v66
	v_fma_f32 v135, v113, v121, v68
	v_mul_f32_e32 v66, v114, v76
	v_mul_f32_e32 v68, v106, v76
	v_fma_f32 v136, v106, v122, -v66
	v_fma_f32 v137, v114, v122, v68
	v_mul_f32_e32 v66, v115, v77
	v_mul_f32_e32 v68, v107, v77
	v_fma_f32 v138, v107, v123, -v66
	v_fma_f32 v139, v115, v123, v68
	ds_read_b128 v[100:103], v90 offset:32
	ds_read_b128 v[104:107], v90 offset:48
	ds_read_b128 v[108:111], v90 offset:4128
	ds_read_b128 v[112:115], v90 offset:4144
	v_add_u32_e32 v78, 0x200, v89
	v_add_u32_e32 v79, 0x1000, v78
	ds_read2_b32 v[116:117], v78 offset0:0 offset1:16
	ds_read2_b32 v[118:119], v78 offset0:32 offset1:48
	ds_read2_b32 v[120:121], v78 offset0:64 offset1:80
	ds_read2_b32 v[122:123], v78 offset0:96 offset1:112
	ds_read2_b32 v[70:71], v79 offset0:0 offset1:16
	ds_read2_b32 v[72:73], v79 offset0:32 offset1:48
	ds_read2_b32 v[74:75], v79 offset0:64 offset1:80
	ds_read2_b32 v[76:77], v79 offset0:96 offset1:112
	s_waitcnt lgkmcnt(0)
	v_mul_f32_e32 v66, v108, v70
	v_mul_f32_e32 v68, v100, v70
	v_fma_f32 v140, v100, v116, -v66
	v_fma_f32 v141, v108, v116, v68
	v_mul_f32_e32 v66, v109, v71
	v_mul_f32_e32 v68, v101, v71
	v_fma_f32 v142, v101, v117, -v66
	v_fma_f32 v143, v109, v117, v68
	v_mul_f32_e32 v66, v110, v72
	v_mul_f32_e32 v68, v102, v72
	v_fma_f32 v144, v102, v118, -v66
	v_fma_f32 v145, v110, v118, v68
	v_mul_f32_e32 v66, v111, v73
	v_mul_f32_e32 v68, v103, v73
	v_fma_f32 v146, v103, v119, -v66
	v_fma_f32 v147, v111, v119, v68
	v_mul_f32_e32 v66, v112, v74
	v_mul_f32_e32 v68, v104, v74
	v_fma_f32 v148, v104, v120, -v66
	v_fma_f32 v149, v112, v120, v68
	v_mul_f32_e32 v66, v113, v75
	v_mul_f32_e32 v68, v105, v75
	v_fma_f32 v150, v105, v121, -v66
	v_fma_f32 v151, v113, v121, v68
	v_mul_f32_e32 v66, v114, v76
	v_mul_f32_e32 v68, v106, v76
	v_fma_f32 v152, v106, v122, -v66
	v_fma_f32 v80, v114, v122, v68
	v_mul_f32_e32 v66, v115, v77
	v_mul_f32_e32 v68, v107, v77
	v_fma_f32 v154, v107, v123, -v66
	v_fma_f32 v155, v115, v123, v68
	ds_read_b128 v[100:103], v90 offset:64
	ds_read_b128 v[104:107], v90 offset:80
	ds_read_b128 v[108:111], v90 offset:4160
	ds_read_b128 v[112:115], v90 offset:4176
	v_add_u32_e32 v78, 0x400, v89
	v_add_u32_e32 v79, 0x1000, v78
	ds_read2_b32 v[116:117], v78 offset0:0 offset1:16
	ds_read2_b32 v[118:119], v78 offset0:32 offset1:48
	ds_read2_b32 v[120:121], v78 offset0:64 offset1:80
	ds_read2_b32 v[122:123], v78 offset0:96 offset1:112
	ds_read2_b32 v[70:71], v79 offset0:0 offset1:16
	ds_read2_b32 v[72:73], v79 offset0:32 offset1:48
	ds_read2_b32 v[74:75], v79 offset0:64 offset1:80
	ds_read2_b32 v[76:77], v79 offset0:96 offset1:112
	s_waitcnt lgkmcnt(0)
	v_mul_f32_e32 v66, v108, v70
	v_mul_f32_e32 v68, v100, v70
	v_fma_f32 v156, v100, v116, -v66
	v_fma_f32 v157, v108, v116, v68
	v_mul_f32_e32 v66, v109, v71
	v_mul_f32_e32 v68, v101, v71
	v_fma_f32 v158, v101, v117, -v66
	v_fma_f32 v159, v109, v117, v68
	v_mul_f32_e32 v66, v110, v72
	v_mul_f32_e32 v68, v102, v72
	v_fma_f32 v160, v102, v118, -v66
	v_fma_f32 v161, v110, v118, v68
	v_mul_f32_e32 v66, v111, v73
	v_mul_f32_e32 v68, v103, v73
	v_fma_f32 v162, v103, v119, -v66
	v_fma_f32 v163, v111, v119, v68
	v_mul_f32_e32 v66, v112, v74
	v_mul_f32_e32 v68, v104, v74
	v_fma_f32 v164, v104, v120, -v66
	v_fma_f32 v165, v112, v120, v68
	v_mul_f32_e32 v66, v113, v75
	v_mul_f32_e32 v68, v105, v75
	v_fma_f32 v166, v105, v121, -v66
	v_fma_f32 v167, v113, v121, v68
	v_mul_f32_e32 v66, v114, v76
	v_mul_f32_e32 v68, v106, v76
	v_fma_f32 v168, v106, v122, -v66
	v_fma_f32 v169, v114, v122, v68
	v_mul_f32_e32 v66, v115, v77
	v_mul_f32_e32 v68, v107, v77
	v_fma_f32 v170, v107, v123, -v66
	v_fma_f32 v171, v115, v123, v68
	ds_read_b128 v[100:103], v90 offset:96
	ds_read_b128 v[104:107], v90 offset:112
	ds_read_b128 v[108:111], v90 offset:4192
	ds_read_b128 v[112:115], v90 offset:4208
	v_add_u32_e32 v78, 0x600, v89
	v_add_u32_e32 v79, 0x1000, v78
	ds_read2_b32 v[116:117], v78 offset0:0 offset1:16
	ds_read2_b32 v[118:119], v78 offset0:32 offset1:48
	ds_read2_b32 v[120:121], v78 offset0:64 offset1:80
	ds_read2_b32 v[122:123], v78 offset0:96 offset1:112
	ds_read2_b32 v[70:71], v79 offset0:0 offset1:16
	ds_read2_b32 v[72:73], v79 offset0:32 offset1:48
	ds_read2_b32 v[74:75], v79 offset0:64 offset1:80
	ds_read2_b32 v[76:77], v79 offset0:96 offset1:112
	s_waitcnt lgkmcnt(0)
	v_mul_f32_e32 v66, v108, v70
	v_mul_f32_e32 v68, v100, v70
	v_fma_f32 v172, v100, v116, -v66
	v_fma_f32 v81, v108, v116, v68
	v_mul_f32_e32 v66, v109, v71
	v_mul_f32_e32 v68, v101, v71
	v_fma_f32 v174, v101, v117, -v66
	v_fma_f32 v175, v109, v117, v68
	v_mul_f32_e32 v66, v110, v72
	v_mul_f32_e32 v68, v102, v72
	v_fma_f32 v176, v102, v118, -v66
	v_fma_f32 v177, v110, v118, v68
	v_mul_f32_e32 v66, v111, v73
	v_mul_f32_e32 v68, v103, v73
	v_fma_f32 v178, v103, v119, -v66
	v_fma_f32 v179, v111, v119, v68
	v_mul_f32_e32 v66, v112, v74
	v_mul_f32_e32 v68, v104, v74
	v_fma_f32 v180, v104, v120, -v66
	v_fma_f32 v181, v112, v120, v68
	v_mul_f32_e32 v66, v113, v75
	v_mul_f32_e32 v68, v105, v75
	v_fma_f32 v182, v105, v121, -v66
	v_fma_f32 v183, v113, v121, v68
	v_mul_f32_e32 v66, v114, v76
	v_mul_f32_e32 v68, v106, v76
	v_fma_f32 v184, v106, v122, -v66
	v_fma_f32 v185, v114, v122, v68
	v_mul_f32_e32 v66, v115, v77
	v_mul_f32_e32 v68, v107, v77
	v_fma_f32 v186, v107, v123, -v66
	v_fma_f32 v187, v115, v123, v68
	ds_read_b128 v[100:103], v90 offset:128
	ds_read_b128 v[104:107], v90 offset:144
	ds_read_b128 v[108:111], v90 offset:4224
	ds_read_b128 v[112:115], v90 offset:4240
	v_add_u32_e32 v78, 0x800, v89
	v_add_u32_e32 v79, 0x1000, v78
	ds_read2_b32 v[116:117], v78 offset0:0 offset1:16
	ds_read2_b32 v[118:119], v78 offset0:32 offset1:48
	ds_read2_b32 v[120:121], v78 offset0:64 offset1:80
	ds_read2_b32 v[122:123], v78 offset0:96 offset1:112
	ds_read2_b32 v[70:71], v79 offset0:0 offset1:16
	ds_read2_b32 v[72:73], v79 offset0:32 offset1:48
	ds_read2_b32 v[74:75], v79 offset0:64 offset1:80
	ds_read2_b32 v[76:77], v79 offset0:96 offset1:112
	s_waitcnt lgkmcnt(0)
	v_mul_f32_e32 v66, v108, v70
	v_mul_f32_e32 v68, v100, v70
	v_fma_f32 v188, v100, v116, -v66
	v_fma_f32 v189, v108, v116, v68
	v_mul_f32_e32 v66, v109, v71
	v_mul_f32_e32 v68, v101, v71
	v_fma_f32 v190, v101, v117, -v66
	v_fma_f32 v191, v109, v117, v68
	v_mul_f32_e32 v66, v110, v72
	v_mul_f32_e32 v68, v102, v72
	v_fma_f32 v192, v102, v118, -v66
	v_fma_f32 v193, v110, v118, v68
	v_mul_f32_e32 v66, v111, v73
	v_mul_f32_e32 v68, v103, v73
	v_fma_f32 v194, v103, v119, -v66
	v_fma_f32 v195, v111, v119, v68
	v_mul_f32_e32 v66, v112, v74
	v_mul_f32_e32 v68, v104, v74
	v_fma_f32 v196, v104, v120, -v66
	v_fma_f32 v197, v112, v120, v68
	v_mul_f32_e32 v66, v113, v75
	v_mul_f32_e32 v68, v105, v75
	v_fma_f32 v198, v105, v121, -v66
	v_fma_f32 v199, v113, v121, v68
	v_mul_f32_e32 v66, v114, v76
	v_mul_f32_e32 v68, v106, v76
	v_fma_f32 v200, v106, v122, -v66
	v_fma_f32 v201, v114, v122, v68
	v_mul_f32_e32 v66, v115, v77
	v_mul_f32_e32 v68, v107, v77
	v_fma_f32 v202, v107, v123, -v66
	v_fma_f32 v203, v115, v123, v68
	ds_read_b128 v[100:103], v90 offset:160
	ds_read_b128 v[104:107], v90 offset:176
	ds_read_b128 v[108:111], v90 offset:4256
	ds_read_b128 v[112:115], v90 offset:4272
	v_add_u32_e32 v78, 0xa00, v89
	v_add_u32_e32 v79, 0x1000, v78
	ds_read2_b32 v[116:117], v78 offset0:0 offset1:16
	ds_read2_b32 v[118:119], v78 offset0:32 offset1:48
	ds_read2_b32 v[120:121], v78 offset0:64 offset1:80
	ds_read2_b32 v[122:123], v78 offset0:96 offset1:112
	ds_read2_b32 v[70:71], v79 offset0:0 offset1:16
	ds_read2_b32 v[72:73], v79 offset0:32 offset1:48
	ds_read2_b32 v[74:75], v79 offset0:64 offset1:80
	ds_read2_b32 v[76:77], v79 offset0:96 offset1:112
	s_waitcnt lgkmcnt(0)
	v_mul_f32_e32 v66, v108, v70
	v_mul_f32_e32 v68, v100, v70
	v_fma_f32 v204, v100, v116, -v66
	v_fma_f32 v205, v108, v116, v68
	v_mul_f32_e32 v66, v109, v71
	v_mul_f32_e32 v68, v101, v71
	v_fma_f32 v206, v101, v117, -v66
	v_fma_f32 v207, v109, v117, v68
	v_mul_f32_e32 v66, v110, v72
	v_mul_f32_e32 v68, v102, v72
	v_fma_f32 v208, v102, v118, -v66
	v_fma_f32 v209, v110, v118, v68
	v_mul_f32_e32 v66, v111, v73
	v_mul_f32_e32 v68, v103, v73
	v_fma_f32 v210, v103, v119, -v66
	v_fma_f32 v211, v111, v119, v68
	v_mul_f32_e32 v66, v112, v74
	v_mul_f32_e32 v68, v104, v74
	v_fma_f32 v212, v104, v120, -v66
	v_fma_f32 v213, v112, v120, v68
	v_mul_f32_e32 v66, v113, v75
	v_mul_f32_e32 v68, v105, v75
	v_fma_f32 v214, v105, v121, -v66
	v_fma_f32 v215, v113, v121, v68
	v_mul_f32_e32 v66, v114, v76
	v_mul_f32_e32 v68, v106, v76
	v_fma_f32 v216, v106, v122, -v66
	v_fma_f32 v217, v114, v122, v68
	v_mul_f32_e32 v66, v115, v77
	v_mul_f32_e32 v68, v107, v77
	v_fma_f32 v218, v107, v123, -v66
	v_fma_f32 v219, v115, v123, v68
	ds_read_b128 v[100:103], v90 offset:192
	ds_read_b128 v[104:107], v90 offset:208
	ds_read_b128 v[108:111], v90 offset:4288
	ds_read_b128 v[112:115], v90 offset:4304
	v_add_u32_e32 v78, 0xc00, v89
	v_add_u32_e32 v79, 0x1000, v78
	ds_read2_b32 v[116:117], v78 offset0:0 offset1:16
	ds_read2_b32 v[118:119], v78 offset0:32 offset1:48
	ds_read2_b32 v[120:121], v78 offset0:64 offset1:80
	ds_read2_b32 v[122:123], v78 offset0:96 offset1:112
	ds_read2_b32 v[70:71], v79 offset0:0 offset1:16
	ds_read2_b32 v[72:73], v79 offset0:32 offset1:48
	ds_read2_b32 v[74:75], v79 offset0:64 offset1:80
	ds_read2_b32 v[76:77], v79 offset0:96 offset1:112
	s_waitcnt lgkmcnt(0)
	v_mul_f32_e32 v66, v108, v70
	v_mul_f32_e32 v68, v100, v70
	v_fma_f32 v220, v100, v116, -v66
	v_fma_f32 v221, v108, v116, v68
	v_mul_f32_e32 v66, v109, v71
	v_mul_f32_e32 v68, v101, v71
	v_fma_f32 v222, v101, v117, -v66
	v_fma_f32 v223, v109, v117, v68
	v_mul_f32_e32 v66, v110, v72
	v_mul_f32_e32 v68, v102, v72
	v_fma_f32 v224, v102, v118, -v66
	v_fma_f32 v225, v110, v118, v68
	v_mul_f32_e32 v66, v111, v73
	v_mul_f32_e32 v68, v103, v73
	v_fma_f32 v226, v103, v119, -v66
	v_fma_f32 v227, v111, v119, v68
	v_mul_f32_e32 v66, v112, v74
	v_mul_f32_e32 v68, v104, v74
	v_fma_f32 v228, v104, v120, -v66
	v_fma_f32 v229, v112, v120, v68
	v_mul_f32_e32 v66, v113, v75
	v_mul_f32_e32 v68, v105, v75
	v_fma_f32 v230, v105, v121, -v66
	v_fma_f32 v231, v113, v121, v68
	v_mul_f32_e32 v66, v114, v76
	v_mul_f32_e32 v68, v106, v76
	v_fma_f32 v232, v106, v122, -v66
	v_fma_f32 v233, v114, v122, v68
	v_mul_f32_e32 v66, v115, v77
	v_mul_f32_e32 v68, v107, v77
	v_fma_f32 v234, v107, v123, -v66
	v_fma_f32 v235, v115, v123, v68
	ds_read_b128 v[100:103], v90 offset:224
	ds_read_b128 v[104:107], v90 offset:240
	ds_read_b128 v[108:111], v90 offset:4320
	ds_read_b128 v[112:115], v90 offset:4336
	v_add_u32_e32 v78, 0xe00, v89
	v_add_u32_e32 v79, 0x1000, v78
	ds_read2_b32 v[116:117], v78 offset0:0 offset1:16
	ds_read2_b32 v[118:119], v78 offset0:32 offset1:48
	ds_read2_b32 v[120:121], v78 offset0:64 offset1:80
	ds_read2_b32 v[122:123], v78 offset0:96 offset1:112
	ds_read2_b32 v[70:71], v79 offset0:0 offset1:16
	ds_read2_b32 v[72:73], v79 offset0:32 offset1:48
	ds_read2_b32 v[74:75], v79 offset0:64 offset1:80
	ds_read2_b32 v[76:77], v79 offset0:96 offset1:112
	s_waitcnt lgkmcnt(0)
	v_mul_f32_e32 v66, v108, v70
	v_mul_f32_e32 v68, v100, v70
	v_fma_f32 v236, v100, v116, -v66
	v_fma_f32 v237, v108, v116, v68
	v_mul_f32_e32 v66, v109, v71
	v_mul_f32_e32 v68, v101, v71
	v_fma_f32 v238, v101, v117, -v66
	v_fma_f32 v239, v109, v117, v68
	v_mul_f32_e32 v66, v110, v72
	v_mul_f32_e32 v68, v102, v72
	v_fma_f32 v240, v102, v118, -v66
	v_fma_f32 v241, v110, v118, v68
	v_mul_f32_e32 v66, v111, v73
	v_mul_f32_e32 v68, v103, v73
	v_fma_f32 v242, v103, v119, -v66
	v_fma_f32 v243, v111, v119, v68
	v_mul_f32_e32 v66, v112, v74
	v_mul_f32_e32 v68, v104, v74
	v_fma_f32 v244, v104, v120, -v66
	v_fma_f32 v245, v112, v120, v68
	v_mul_f32_e32 v66, v113, v75
	v_mul_f32_e32 v68, v105, v75
	v_fma_f32 v246, v105, v121, -v66
	v_fma_f32 v247, v113, v121, v68
	v_mul_f32_e32 v66, v114, v76
	v_mul_f32_e32 v68, v106, v76
	v_fma_f32 v248, v106, v122, -v66
	v_fma_f32 v249, v114, v122, v68
	v_mul_f32_e32 v66, v115, v77
	v_mul_f32_e32 v68, v107, v77
	v_fma_f32 v250, v107, v123, -v66
	v_fma_f32 v251, v115, v123, v68
	s_nop 0
	s_nop 0
	s_nop 0
	s_nop 0
	s_nop 0
	s_nop 0
	s_nop 0
	s_nop 0
	s_nop 0
	s_nop 0
	s_nop 0
	s_nop 0
	s_nop 0
	s_nop 0
	s_nop 0
	s_nop 0
	s_nop 0
	s_nop 0
	s_nop 0
	s_nop 0
	s_nop 0
	s_nop 0
	s_nop 0
	s_nop 0
	s_nop 0
	s_nop 0
	s_nop 0
	s_nop 0
	s_nop 0
	s_nop 0
	s_nop 0
	s_nop 0
	s_nop 0
	s_nop 0
	s_nop 0
	s_nop 0
	s_nop 0
	s_nop 0
	s_nop 0
	s_nop 0
	s_nop 0
	s_nop 0
	s_nop 0
	s_nop 0
	s_nop 0
	s_nop 0
	s_nop 0
	s_nop 0
	s_nop 0
	s_nop 0
	s_branch .LBB0_33
